# seam: non-leader arrival-counter poll back-off s_sleep 6 -> 16
# baseline (speedup 1.0000x reference)
.LBB0_823:
	s_and_b32 s1, s0, 0xff
	s_mov_b64 s[20:21], -1
	s_cmp_lg_u32 s1, 0
	s_mov_b64 s[26:27], -1
	s_sleep 16
	s_cbranch_scc0 .LBB0_826
	s_and_b64 vcc, exec, s[26:27]
	s_cbranch_vccz .LBB0_822
